# placement: attention loops shifted by 8 bytes, later loops unchanged
# speedup vs baseline: 1.0019x; 1.0019x over previous
.LBB0_581:
	s_cmp_lt_u32 s3, 0x400001
	s_mov_b64 s[24:25], 0
	s_cselect_b64 s[28:29], -1, 0
	s_and_b64 vcc, exec, s[28:29]
	s_cbranch_vccz .LBB0_575
	s_branch .LBB0_580
	s_nop 0
	s_nop 0

.LBB0_713:
	s_andn2_b64 vcc, exec, s[76:77]
	s_waitcnt vmcnt(0) lgkmcnt(0)
	s_barrier
	s_cbranch_vccnz .LBB0_656
	ds_read2st64_b32 v[66:67], v64 offset1:1
	ds_read2st64_b32 v[76:77], v64 offset0:2 offset1:3
	ds_read2st64_b32 v[78:79], v64 offset0:4 offset1:5
	ds_read2st64_b32 v[80:81], v64 offset0:6 offset1:7
	ds_read2st64_b32 v[82:83], v64 offset0:8 offset1:9
	ds_read2st64_b32 v[84:85], v64 offset0:10 offset1:11
	ds_read2st64_b32 v[86:87], v64 offset0:12 offset1:13
	ds_read2st64_b32 v[88:89], v64 offset0:14 offset1:15
	ds_read2st64_b32 v[90:91], v64 offset0:16 offset1:17
	ds_read2st64_b32 v[116:117], v64 offset0:18 offset1:19
	ds_read2st64_b32 v[118:119], v64 offset0:20 offset1:21
	ds_read2st64_b32 v[120:121], v64 offset0:22 offset1:23
	ds_read2st64_b32 v[122:123], v64 offset0:24 offset1:25
	ds_read2st64_b32 v[124:125], v64 offset0:26 offset1:27
	ds_read2st64_b32 v[126:127], v64 offset0:28 offset1:29
	ds_read2st64_b32 v[128:129], v64 offset0:30 offset1:31
	ds_read2st64_b32 v[130:131], v64 offset0:32 offset1:33
	ds_read2st64_b32 v[132:133], v64 offset0:34 offset1:35
	ds_read2st64_b32 v[134:135], v64 offset0:36 offset1:37
	ds_read2st64_b32 v[136:137], v64 offset0:38 offset1:39
	ds_read2st64_b32 v[138:139], v64 offset0:40 offset1:41
	ds_read2st64_b32 v[140:141], v64 offset0:42 offset1:43
	ds_read2st64_b32 v[142:143], v64 offset0:44 offset1:45
	ds_read2st64_b32 v[148:149], v64 offset0:46 offset1:47
	ds_read2st64_b32 v[68:69], v64 offset0:58 offset1:59
	ds_read2st64_b32 v[150:151], v64 offset0:48 offset1:49
	ds_read2st64_b32 v[152:153], v64 offset0:50 offset1:51
	ds_read2st64_b32 v[154:155], v64 offset0:52 offset1:53
	ds_read2st64_b32 v[156:157], v64 offset0:54 offset1:55
	ds_read2st64_b32 v[72:73], v64 offset0:60 offset1:61
	ds_read2st64_b32 v[96:97], v64 offset0:62 offset1:63
	ds_read2st64_b32 v[162:163], v64 offset0:56 offset1:57
	s_waitcnt lgkmcnt(14)
	v_pk_fma_f32 v[98:99], v[50:51], v[74:75], v[76:77] op_sel_hi:[1,0,1] neg_lo:[0,0,1] neg_hi:[0,0,1]
	v_pk_fma_f32 v[104:105], v[48:49], v[74:75], v[66:67] op_sel_hi:[1,0,1] neg_lo:[0,0,1] neg_hi:[0,0,1]
	global_load_dwordx4 v[64:67], v146, s[30:31]
	global_load_dwordx4 v[48:51], v146, s[30:31] offset:32
	v_pk_mul_f32 v[164:165], v[104:105], v[104:105]
	s_waitcnt lgkmcnt(7)
	v_pk_fma_f32 v[70:71], v[26:27], v[74:75], v[68:69] op_sel_hi:[1,0,1] neg_lo:[0,0,1] neg_hi:[0,0,1]
	s_waitcnt lgkmcnt(2)
	v_pk_fma_f32 v[68:69], v[28:29], v[74:75], v[72:73] op_sel_hi:[1,0,1] neg_lo:[0,0,1] neg_hi:[0,0,1]
	s_waitcnt lgkmcnt(1)
	v_pk_fma_f32 v[72:73], v[30:31], v[74:75], v[96:97] op_sel_hi:[1,0,1] neg_lo:[0,0,1] neg_hi:[0,0,1]
	v_or_b32_e32 v26, s34, v161
	v_pk_mul_f32 v[160:161], v[98:99], v[98:99]
	v_pk_fma_f32 v[102:103], v[54:55], v[74:75], v[80:81] op_sel_hi:[1,0,1] neg_lo:[0,0,1] neg_hi:[0,0,1]
	v_pk_fma_f32 v[108:109], v[52:53], v[74:75], v[78:79] op_sel_hi:[1,0,1] neg_lo:[0,0,1] neg_hi:[0,0,1]
	v_pk_fma_f32 v[106:107], v[58:59], v[74:75], v[84:85] op_sel_hi:[1,0,1] neg_lo:[0,0,1] neg_hi:[0,0,1]
	v_pk_fma_f32 v[112:113], v[56:57], v[74:75], v[82:83] op_sel_hi:[1,0,1] neg_lo:[0,0,1] neg_hi:[0,0,1]
	v_pk_fma_f32 v[110:111], v[62:63], v[74:75], v[88:89] op_sel_hi:[1,0,1] neg_lo:[0,0,1] neg_hi:[0,0,1]
	v_pk_fma_f32 v[114:115], v[60:61], v[74:75], v[86:87] op_sel_hi:[1,0,1] neg_lo:[0,0,1] neg_hi:[0,0,1]
	v_pk_fma_f32 v[60:61], v[2:3], v[74:75], v[116:117] op_sel_hi:[1,0,1] neg_lo:[0,0,1] neg_hi:[0,0,1]
	v_pk_fma_f32 v[62:63], v[0:1], v[74:75], v[90:91] op_sel_hi:[1,0,1] neg_lo:[0,0,1] neg_hi:[0,0,1]
	v_pk_fma_f32 v[76:77], v[6:7], v[74:75], v[120:121] op_sel_hi:[1,0,1] neg_lo:[0,0,1] neg_hi:[0,0,1]
	v_pk_fma_f32 v[80:81], v[4:5], v[74:75], v[118:119] op_sel_hi:[1,0,1] neg_lo:[0,0,1] neg_hi:[0,0,1]
	v_pk_fma_f32 v[78:79], v[10:11], v[74:75], v[124:125] op_sel_hi:[1,0,1] neg_lo:[0,0,1] neg_hi:[0,0,1]
	v_pk_fma_f32 v[82:83], v[8:9], v[74:75], v[122:123] op_sel_hi:[1,0,1] neg_lo:[0,0,1] neg_hi:[0,0,1]
	v_pk_fma_f32 v[84:85], v[14:15], v[74:75], v[128:129] op_sel_hi:[1,0,1] neg_lo:[0,0,1] neg_hi:[0,0,1]
	v_pk_fma_f32 v[86:87], v[12:13], v[74:75], v[126:127] op_sel_hi:[1,0,1] neg_lo:[0,0,1] neg_hi:[0,0,1]
	v_pk_fma_f32 v[34:35], v[34:35], v[74:75], v[132:133] op_sel_hi:[1,0,1] neg_lo:[0,0,1] neg_hi:[0,0,1]
	v_pk_fma_f32 v[88:89], v[32:33], v[74:75], v[130:131] op_sel_hi:[1,0,1] neg_lo:[0,0,1] neg_hi:[0,0,1]
	v_pk_fma_f32 v[38:39], v[38:39], v[74:75], v[136:137] op_sel_hi:[1,0,1] neg_lo:[0,0,1] neg_hi:[0,0,1]
	v_pk_fma_f32 v[90:91], v[36:37], v[74:75], v[134:135] op_sel_hi:[1,0,1] neg_lo:[0,0,1] neg_hi:[0,0,1]
	v_pk_fma_f32 v[36:37], v[42:43], v[74:75], v[140:141] op_sel_hi:[1,0,1] neg_lo:[0,0,1] neg_hi:[0,0,1]
	v_pk_fma_f32 v[42:43], v[40:41], v[74:75], v[138:139] op_sel_hi:[1,0,1] neg_lo:[0,0,1] neg_hi:[0,0,1]
	v_pk_fma_f32 v[40:41], v[46:47], v[74:75], v[148:149] op_sel_hi:[1,0,1] neg_lo:[0,0,1] neg_hi:[0,0,1]
	v_pk_fma_f32 v[44:45], v[44:45], v[74:75], v[142:143] op_sel_hi:[1,0,1] neg_lo:[0,0,1] neg_hi:[0,0,1]
	v_pk_fma_f32 v[18:19], v[18:19], v[74:75], v[152:153] op_sel_hi:[1,0,1] neg_lo:[0,0,1] neg_hi:[0,0,1]
	v_pk_fma_f32 v[46:47], v[16:17], v[74:75], v[150:151] op_sel_hi:[1,0,1] neg_lo:[0,0,1] neg_hi:[0,0,1]
	v_pk_fma_f32 v[16:17], v[22:23], v[74:75], v[156:157] op_sel_hi:[1,0,1] neg_lo:[0,0,1] neg_hi:[0,0,1]
	v_pk_fma_f32 v[20:21], v[20:21], v[74:75], v[154:155] op_sel_hi:[1,0,1] neg_lo:[0,0,1] neg_hi:[0,0,1]
	s_waitcnt lgkmcnt(0)
	v_pk_fma_f32 v[22:23], v[24:25], v[74:75], v[162:163] op_sel_hi:[1,0,1] neg_lo:[0,0,1] neg_hi:[0,0,1]
	v_add_f32_e32 v74, v164, v165
	v_add_f32_e32 v74, v74, v160
	v_pk_mul_f32 v[168:169], v[108:109], v[108:109]
	v_add_f32_e32 v74, v74, v161
	v_add_f32_e32 v74, v74, v168
	v_pk_mul_f32 v[166:167], v[102:103], v[102:103]
	v_add_f32_e32 v74, v74, v169
	global_load_dwordx4 v[56:59], v146, s[30:31] offset:64
	global_load_dwordx4 v[52:55], v146, s[30:31] offset:96
	v_add_f32_e32 v74, v74, v166
	v_pk_mul_f32 v[172:173], v[112:113], v[112:113]
	v_add_f32_e32 v74, v74, v167
	v_add_f32_e32 v74, v74, v172
	v_pk_mul_f32 v[170:171], v[106:107], v[106:107]
	v_add_f32_e32 v74, v74, v173
	v_add_f32_e32 v74, v74, v170
	v_pk_mul_f32 v[178:179], v[114:115], v[114:115]
	v_add_f32_e32 v74, v74, v171
	v_add_f32_e32 v74, v74, v178
	v_pk_mul_f32 v[174:175], v[110:111], v[110:111]
	v_add_f32_e32 v74, v74, v179
	v_add_f32_e32 v74, v74, v174
	v_pk_mul_f32 v[180:181], v[62:63], v[62:63]
	v_add_f32_e32 v74, v74, v175
	v_add_f32_e32 v74, v74, v180
	v_pk_mul_f32 v[116:117], v[60:61], v[60:61]
	v_add_f32_e32 v74, v74, v181
	v_add_f32_e32 v74, v74, v116
	v_pk_mul_f32 v[118:119], v[80:81], v[80:81]
	v_add_f32_e32 v74, v74, v117
	v_add_f32_e32 v74, v74, v118
	v_pk_mul_f32 v[120:121], v[76:77], v[76:77]
	v_add_f32_e32 v74, v74, v119
	v_add_f32_e32 v74, v74, v120
	v_pk_mul_f32 v[122:123], v[82:83], v[82:83]
	v_add_f32_e32 v74, v74, v121
	v_add_f32_e32 v74, v74, v122
	v_pk_mul_f32 v[124:125], v[78:79], v[78:79]
	v_add_f32_e32 v74, v74, v123
	v_add_f32_e32 v74, v74, v124
	v_pk_mul_f32 v[126:127], v[86:87], v[86:87]
	v_add_f32_e32 v74, v74, v125
	v_add_f32_e32 v74, v74, v126
	v_pk_mul_f32 v[128:129], v[84:85], v[84:85]
	v_add_f32_e32 v74, v74, v127
	v_add_f32_e32 v74, v74, v128
	v_pk_mul_f32 v[130:131], v[88:89], v[88:89]
	v_add_f32_e32 v74, v74, v129
	v_add_f32_e32 v74, v74, v130
	v_pk_mul_f32 v[132:133], v[34:35], v[34:35]
	v_add_f32_e32 v74, v74, v131
	v_add_f32_e32 v74, v74, v132
	v_pk_mul_f32 v[134:135], v[90:91], v[90:91]
	v_add_f32_e32 v74, v74, v133
	v_add_f32_e32 v74, v74, v134
	v_pk_mul_f32 v[136:137], v[38:39], v[38:39]
	v_add_f32_e32 v74, v74, v135
	v_add_f32_e32 v74, v74, v136
	v_pk_mul_f32 v[138:139], v[42:43], v[42:43]
	v_add_f32_e32 v74, v74, v137
	v_add_f32_e32 v74, v74, v138
	v_pk_mul_f32 v[140:141], v[36:37], v[36:37]
	v_add_f32_e32 v74, v74, v139
	v_add_f32_e32 v74, v74, v140
	v_pk_mul_f32 v[142:143], v[44:45], v[44:45]
	v_add_f32_e32 v74, v74, v141
	v_add_f32_e32 v74, v74, v142
	v_pk_mul_f32 v[148:149], v[40:41], v[40:41]
	v_add_f32_e32 v74, v74, v143
	v_add_f32_e32 v74, v74, v148
	v_pk_mul_f32 v[150:151], v[46:47], v[46:47]
	v_add_f32_e32 v74, v74, v149
	v_add_f32_e32 v74, v74, v150
	v_pk_mul_f32 v[152:153], v[18:19], v[18:19]
	v_add_f32_e32 v74, v74, v151
	v_add_f32_e32 v74, v74, v152
	v_pk_mul_f32 v[154:155], v[20:21], v[20:21]
	v_add_f32_e32 v74, v74, v153
	v_add_f32_e32 v74, v74, v154
	v_pk_mul_f32 v[156:157], v[16:17], v[16:17]
	v_add_f32_e32 v74, v74, v155
	v_ashrrev_i32_e32 v27, 31, v26
	v_readlane_b32 s0, v255, 20
	v_add_f32_e32 v74, v74, v156
	v_lshlrev_b64 v[26:27], 12, v[26:27]
	v_readlane_b32 s1, v255, 21
	v_pk_mul_f32 v[24:25], v[22:23], v[22:23]
	v_add_f32_e32 v74, v74, v157
	v_lshl_add_u64 v[26:27], s[0:1], 0, v[26:27]
	v_add_f32_e32 v24, v74, v24
	v_pk_mul_f32 v[92:93], v[70:71], v[70:71]
	v_lshl_add_u64 v[100:101], v[26:27], 0, s[72:73]
	global_load_dwordx4 v[26:29], v146, s[30:31] offset:128
	global_load_dwordx4 v[0:3], v146, s[30:31] offset:160
	v_add_f32_e32 v24, v24, v25
	v_add_f32_e32 v24, v24, v92
	v_pk_mul_f32 v[94:95], v[68:69], v[68:69]
	v_add_f32_e32 v24, v24, v93
	v_add_f32_e32 v24, v24, v94
	v_pk_mul_f32 v[96:97], v[72:73], v[72:73]
	v_add_f32_e32 v24, v24, v95
	v_add_f32_e32 v24, v24, v96
	v_add_f32_e32 v74, v24, v97
	ds_bpermute_b32 v75, v75, v74
	global_load_dwordx4 v[8:11], v146, s[30:31] offset:192
	global_load_dwordx4 v[4:7], v146, s[30:31] offset:224
	global_load_dwordx4 v[30:33], v146, s[30:31] offset:256
	global_load_dwordx4 v[12:15], v146, s[30:31] offset:288
	global_load_dwordx4 v[92:95], v146, s[30:31] offset:320
	global_load_dwordx4 v[116:119], v146, s[30:31] offset:352
	v_lshlrev_b32_e32 v176, 3, v158
	s_waitcnt lgkmcnt(0)
	v_add_f32_e32 v74, v74, v75
	v_fmamk_f32 v74, v74, 0x3c000000, v213
	v_rsq_f32_e32 v74, v74
	v_lshl_add_u64 v[24:25], v[100:101], 0, v[176:177]
	global_load_dwordx4 v[120:123], v146, s[30:31] offset:384
	global_load_dwordx4 v[124:127], v146, s[30:31] offset:416
	global_load_dwordx4 v[128:131], v146, s[30:31] offset:448
	v_mul_f32_e32 v74, v145, v74
	v_pk_mul_f32 v[96:97], v[104:105], v[74:75] op_sel_hi:[1,0]
	s_waitcnt vmcnt(14)
	v_pk_mul_f32 v[64:65], v[64:65], v[96:97]
	v_pk_mul_f32 v[96:97], v[98:99], v[74:75] op_sel_hi:[1,0]
	v_cvt_pk_bf16_f32 v64, v64, v65
	v_pk_mul_f32 v[66:67], v[66:67], v[96:97]
	s_nop 0
	v_cvt_pk_bf16_f32 v65, v66, v67
	global_store_dwordx2 v[24:25], v[64:65], off
	v_pk_mul_f32 v[64:65], v[108:109], v[74:75] op_sel_hi:[1,0]
	s_waitcnt vmcnt(14)
	v_pk_mul_f32 v[48:49], v[48:49], v[64:65]
	v_pk_mul_f32 v[64:65], v[102:103], v[74:75] op_sel_hi:[1,0]
	v_cvt_pk_bf16_f32 v48, v48, v49
	v_pk_mul_f32 v[50:51], v[50:51], v[64:65]
	s_nop 0
	v_cvt_pk_bf16_f32 v49, v50, v51
	global_store_dwordx2 v[24:25], v[48:49], off offset:16
	v_pk_mul_f32 v[48:49], v[112:113], v[74:75] op_sel_hi:[1,0]
	v_pk_mul_f32 v[50:51], v[106:107], v[74:75] op_sel_hi:[1,0]
	s_waitcnt vmcnt(14)
	v_pk_mul_f32 v[48:49], v[56:57], v[48:49]
	v_pk_mul_f32 v[50:51], v[58:59], v[50:51]
	v_cvt_pk_bf16_f32 v48, v48, v49
	v_cvt_pk_bf16_f32 v49, v50, v51
	global_store_dwordx2 v[24:25], v[48:49], off offset:32
	v_pk_mul_f32 v[48:49], v[114:115], v[74:75] op_sel_hi:[1,0]
	s_waitcnt vmcnt(14)
	v_pk_mul_f32 v[48:49], v[52:53], v[48:49]
	s_nop 0
	v_cvt_pk_bf16_f32 v52, v48, v49
	v_pk_mul_f32 v[48:49], v[110:111], v[74:75] op_sel_hi:[1,0]
	s_nop 0
	v_pk_mul_f32 v[48:49], v[54:55], v[48:49]
	s_nop 0
	v_cvt_pk_bf16_f32 v53, v48, v49
	global_load_dwordx4 v[48:51], v146, s[30:31] offset:480
	s_nop 0
	global_store_dwordx2 v[24:25], v[52:53], off offset:48
	v_pk_mul_f32 v[52:53], v[62:63], v[74:75] op_sel_hi:[1,0]
	s_waitcnt vmcnt(15)
	v_pk_mul_f32 v[26:27], v[52:53], v[26:27]
	v_pk_mul_f32 v[52:53], v[60:61], v[74:75] op_sel_hi:[1,0]
	v_cvt_pk_bf16_f32 v26, v26, v27
	v_pk_mul_f32 v[28:29], v[52:53], v[28:29]
	s_nop 0
	v_cvt_pk_bf16_f32 v27, v28, v29
	global_store_dwordx2 v[24:25], v[26:27], off offset:64
	v_pk_mul_f32 v[26:27], v[80:81], v[74:75] op_sel_hi:[1,0]
	s_waitcnt vmcnt(15)
	v_pk_mul_f32 v[0:1], v[26:27], v[0:1]
	v_pk_mul_f32 v[26:27], v[76:77], v[74:75] op_sel_hi:[1,0]
	v_cvt_pk_bf16_f32 v0, v0, v1
	v_pk_mul_f32 v[2:3], v[26:27], v[2:3]
	s_nop 0
	v_cvt_pk_bf16_f32 v1, v2, v3
	global_store_dwordx2 v[24:25], v[0:1], off offset:80
	v_pk_mul_f32 v[0:1], v[82:83], v[74:75] op_sel_hi:[1,0]
	v_pk_mul_f32 v[2:3], v[78:79], v[74:75] op_sel_hi:[1,0]
	s_waitcnt vmcnt(15)
	v_pk_mul_f32 v[0:1], v[0:1], v[8:9]
	v_pk_mul_f32 v[2:3], v[2:3], v[10:11]
	v_cvt_pk_bf16_f32 v0, v0, v1
	v_cvt_pk_bf16_f32 v1, v2, v3
	global_store_dwordx2 v[24:25], v[0:1], off offset:96
	v_pk_mul_f32 v[0:1], v[86:87], v[74:75] op_sel_hi:[1,0]
	v_pk_mul_f32 v[2:3], v[84:85], v[74:75] op_sel_hi:[1,0]
	s_waitcnt vmcnt(15)
	v_pk_mul_f32 v[0:1], v[0:1], v[4:5]
	v_pk_mul_f32 v[2:3], v[2:3], v[6:7]
	v_cvt_pk_bf16_f32 v0, v0, v1
	v_cvt_pk_bf16_f32 v1, v2, v3
	global_store_dwordx2 v[24:25], v[0:1], off offset:112
	v_pk_mul_f32 v[0:1], v[88:89], v[74:75] op_sel_hi:[1,0]
	v_pk_mul_f32 v[2:3], v[34:35], v[74:75] op_sel_hi:[1,0]
	s_waitcnt vmcnt(15)
	v_pk_mul_f32 v[0:1], v[0:1], v[30:31]
	v_pk_mul_f32 v[2:3], v[2:3], v[32:33]
	v_cvt_pk_bf16_f32 v0, v0, v1
	v_cvt_pk_bf16_f32 v1, v2, v3
	global_store_dwordx2 v[24:25], v[0:1], off offset:128
	v_pk_mul_f32 v[0:1], v[90:91], v[74:75] op_sel_hi:[1,0]
	v_pk_mul_f32 v[2:3], v[38:39], v[74:75] op_sel_hi:[1,0]
	s_waitcnt vmcnt(15)
	v_pk_mul_f32 v[0:1], v[0:1], v[12:13]
	v_pk_mul_f32 v[2:3], v[2:3], v[14:15]
	v_cvt_pk_bf16_f32 v0, v0, v1
	v_cvt_pk_bf16_f32 v1, v2, v3
	global_store_dwordx2 v[24:25], v[0:1], off offset:144
	v_pk_mul_f32 v[0:1], v[42:43], v[74:75] op_sel_hi:[1,0]
	v_pk_mul_f32 v[2:3], v[36:37], v[74:75] op_sel_hi:[1,0]
	s_waitcnt vmcnt(15)
	v_pk_mul_f32 v[0:1], v[0:1], v[92:93]
	v_pk_mul_f32 v[2:3], v[2:3], v[94:95]
	v_cvt_pk_bf16_f32 v0, v0, v1
	v_cvt_pk_bf16_f32 v1, v2, v3
	global_store_dwordx2 v[24:25], v[0:1], off offset:160
	v_pk_mul_f32 v[0:1], v[44:45], v[74:75] op_sel_hi:[1,0]
	v_pk_mul_f32 v[2:3], v[40:41], v[74:75] op_sel_hi:[1,0]
	s_waitcnt vmcnt(15)
	v_pk_mul_f32 v[0:1], v[0:1], v[116:117]
	v_pk_mul_f32 v[2:3], v[2:3], v[118:119]
	v_cvt_pk_bf16_f32 v0, v0, v1
	v_cvt_pk_bf16_f32 v1, v2, v3
	global_store_dwordx2 v[24:25], v[0:1], off offset:176
	v_pk_mul_f32 v[0:1], v[46:47], v[74:75] op_sel_hi:[1,0]
	v_pk_mul_f32 v[2:3], v[18:19], v[74:75] op_sel_hi:[1,0]
	s_waitcnt vmcnt(15)
	v_pk_mul_f32 v[0:1], v[0:1], v[120:121]
	v_pk_mul_f32 v[2:3], v[2:3], v[122:123]
	v_cvt_pk_bf16_f32 v0, v0, v1
	v_cvt_pk_bf16_f32 v1, v2, v3
	global_store_dwordx2 v[24:25], v[0:1], off offset:192
	v_pk_mul_f32 v[0:1], v[20:21], v[74:75] op_sel_hi:[1,0]
	v_pk_mul_f32 v[2:3], v[16:17], v[74:75] op_sel_hi:[1,0]
	s_waitcnt vmcnt(15)
	v_pk_mul_f32 v[0:1], v[0:1], v[124:125]
	v_pk_mul_f32 v[2:3], v[2:3], v[126:127]
	v_cvt_pk_bf16_f32 v0, v0, v1
	v_cvt_pk_bf16_f32 v1, v2, v3
	global_store_dwordx2 v[24:25], v[0:1], off offset:208
	v_pk_mul_f32 v[0:1], v[22:23], v[74:75] op_sel_hi:[1,0]
	v_pk_mul_f32 v[2:3], v[70:71], v[74:75] op_sel_hi:[1,0]
	s_waitcnt vmcnt(15)
	v_pk_mul_f32 v[0:1], v[0:1], v[128:129]
	v_pk_mul_f32 v[2:3], v[2:3], v[130:131]
	v_cvt_pk_bf16_f32 v0, v0, v1
	v_cvt_pk_bf16_f32 v1, v2, v3
	global_store_dwordx2 v[24:25], v[0:1], off offset:224
	v_pk_mul_f32 v[0:1], v[68:69], v[74:75] op_sel_hi:[1,0]
	v_pk_mul_f32 v[2:3], v[72:73], v[74:75] op_sel_hi:[1,0]
	s_waitcnt vmcnt(12)
	v_pk_mul_f32 v[0:1], v[0:1], v[48:49]
	v_pk_mul_f32 v[2:3], v[2:3], v[50:51]
	v_cvt_pk_bf16_f32 v0, v0, v1
	v_cvt_pk_bf16_f32 v1, v2, v3
	global_store_dwordx2 v[24:25], v[0:1], off offset:240
	s_branch .LBB0_656
	s_nop 0
	s_nop 0
	s_nop 0
	s_nop 0
	s_nop 0
	s_nop 0
	s_nop 0
	s_nop 0
.LBB0_715:
	s_cmpk_lg_i32 s8, 0x100
	s_mov_b64 s[0:1], -1
	s_cbranch_scc0 .LBB0_717
	s_abs_i32 s0, s8
	v_cvt_f32_u32_e32 v0, s0
	s_sub_i32 s4, 0, s0
	s_add_i32 s1, s8, 0x7f
	s_ashr_i32 s2, s1, 31
	v_rcp_iflag_f32_e32 v0, v0
	s_abs_i32 s1, s1
	s_ashr_i32 s3, s8, 31
	s_xor_b32 s2, s2, s3
	v_mul_f32_e32 v0, 0x4f7ffffe, v0
	v_cvt_u32_f32_e32 v0, v0
	s_nop 0
	v_readfirstlane_b32 s5, v0
	s_mul_i32 s4, s4, s5
	s_mul_hi_u32 s4, s5, s4
	s_add_i32 s5, s5, s4
	s_mul_hi_u32 s4, s1, s5
	s_mul_i32 s6, s4, s0
	s_sub_i32 s1, s1, s6
	s_add_i32 s7, s4, 1
	s_sub_i32 s6, s1, s0
	s_cmp_ge_u32 s1, s0
	s_cselect_b32 s4, s7, s4
	s_cselect_b32 s1, s6, s1
	s_add_i32 s6, s4, 1
	s_cmp_ge_u32 s1, s0
	s_cselect_b32 s1, s6, s4
	s_xor_b32 s1, s1, s2
	s_sub_i32 s1, s1, s2
	v_readlane_b32 s7, v255, 24
	s_mul_i32 s21, s1, s7
	s_sub_i32 s2, 0x80, s21
	s_min_i32 s1, s2, s1
	s_cmpk_lt_i32 s21, 0x80
	s_cselect_b32 s2, s1, 0
	s_add_i32 s1, s8, 0xff
	s_ashr_i32 s4, s1, 31
	s_abs_i32 s1, s1
	s_xor_b32 s3, s4, s3
	s_mul_hi_u32 s4, s1, s5
	s_mul_i32 s5, s4, s0
	s_sub_i32 s1, s1, s5
	s_add_i32 s5, s4, 1
	s_sub_i32 s6, s1, s0
	s_cmp_ge_u32 s1, s0
	s_cselect_b32 s4, s5, s4
	s_cselect_b32 s1, s6, s1
	s_add_i32 s5, s4, 1
	s_cmp_ge_u32 s1, s0
	s_cselect_b32 s0, s5, s4
	s_xor_b32 s0, s0, s3
	s_sub_i32 s0, s0, s3
	s_mul_i32 s3, s0, s7
	s_sub_i32 s1, 0x100, s3
	s_min_i32 s0, s1, s0
	s_cmpk_lt_i32 s3, 0x100
	s_cselect_b32 s20, s0, 0
	s_mov_b64 s[0:1], 0
